# phase C: barrier-coupled flash passes at s_setprio 1, wave-independent top-k and epilogue at 0
# baseline (speedup 1.0000x reference)
.LBB0_484:
	s_setprio 1
	v_and_b32_e32 v2, 15, v3
	v_bfe_u32 v1, v3, 4, 2
	v_lshlrev_b32_e32 v0, 7, v0
	v_xor_b32_e32 v3, v4, v3
	s_movk_i32 s2, 0x70
	v_and_or_b32 v42, v3, s2, v0
	v_mul_u32_u24_e32 v0, 0x90, v2
	v_lshlrev_b32_e32 v3, 4, v1
	v_add3_u32 v0, v95, v0, v3
	ds_read_b128 v[24:27], v0 offset:32768
	ds_read_b128 v[28:31], v0 offset:32832
	s_cmp_gt_u32 s66, 3
	v_readfirstlane_b32 s67, v107
	v_mov_b32_e32 v32, 0x3f803f80
	s_cselect_b64 s[60:61], -1, 0
	s_cmp_lt_u32 s66, 4
	s_waitcnt vmcnt(11)
	ds_write_b128 v42, v[8:11]
	s_waitcnt vmcnt(10)
	ds_write_b128 v42, v[12:15] offset:8192
	s_waitcnt vmcnt(8)
	ds_write_b128 v42, v[16:19] offset:16384
	ds_write_b128 v42, v[20:23] offset:24576
	s_cbranch_scc1 .LBB0_486
	v_add_co_u32_e32 v4, vcc, 0x4000, v40
	s_nop 1
	v_addc_co_u32_e32 v5, vcc, 0, v41, vcc
	v_add_co_u32_e32 v6, vcc, 0x5000, v40
	s_nop 1
	v_addc_co_u32_e32 v7, vcc, 0, v41, vcc
	global_load_dwordx4 v[8:11], v[4:5], off
	global_load_dwordx4 v[12:15], v[6:7], off
	v_add_co_u32_e32 v4, vcc, 0x6000, v40
	s_nop 1
	v_addc_co_u32_e32 v5, vcc, 0, v41, vcc
	v_add_co_u32_e32 v6, vcc, 0x7000, v40
	s_nop 1
	v_addc_co_u32_e32 v7, vcc, 0, v41, vcc
	global_load_dwordx4 v[16:19], v[4:5], off
	global_load_dwordx4 v[20:23], v[6:7], off

.LBB0_571:
	s_setprio 0
	s_lshl_b32 s2, s72, 19
	s_and_b32 s84, s2, 0x100000
	s_and_b32 s2, s82, -16
	v_subrev_u32_e32 v0, s2, v106
	v_ashrrev_i32_e32 v1, 31, v0
	v_lshlrev_b64 v[0:1], 6, v[0:1]
	v_lshl_add_u64 v[0:1], s[84:85], 0, v[0:1]
	v_cndmask_b32_e64 v3, 0, 1, s[80:81]
	v_lshl_or_b32 v0, v3, 5, v0
	v_mul_u32_u24_e32 v3, 3, v87
	v_lshlrev_b64 v[4:5], 7, v[88:89]
	v_lshl_add_u64 v[4:5], s[40:41], 0, v[4:5]
	v_lshlrev_b32_e32 v128, 2, v3
	v_lshl_add_u64 v[4:5], v[4:5], 0, v[128:129]
	v_lshlrev_b32_e32 v2, 6, v87
	v_lshlrev_b64 v[4:5], 11, v[88:89]
	v_lshl_add_u64 v[4:5], s[38:39], 0, v[4:5]
	v_lshlrev_b32_e32 v128, 2, v2
	v_mov_b32_e32 v87, v129
	v_lshl_add_u64 v[0:1], v[82:83], 0, v[0:1]
	s_mov_b32 s84, 0
	s_waitcnt vmcnt(0)
	v_mul_f32_e32 v3, 0xbfb8aa3b, v136
	v_exp_f32_e32 v3, v3
	s_nop 0
	v_add_f32_e32 v3, 1.0, v3
	v_rcp_f32_e32 v6, v3
	v_lshl_add_u64 v[2:3], v[4:5], 0, v[128:129]
	v_lshl_add_u64 v[8:9], v[2:3], 0, v[86:87]
	v_pk_mul_f32 v[2:3], v[48:49], v[6:7] op_sel_hi:[1,0]
	v_pk_mul_f32 v[4:5], v[50:51], v[6:7] op_sel_hi:[1,0]
	global_store_dwordx4 v[8:9], v[2:5], off
	s_nop 1
	v_pk_mul_f32 v[2:3], v[56:57], v[6:7] op_sel_hi:[1,0]
	v_pk_mul_f32 v[4:5], v[58:59], v[6:7] op_sel_hi:[1,0]
	global_store_dwordx4 v[8:9], v[2:5], off offset:64
	s_nop 1
	v_pk_mul_f32 v[2:3], v[52:53], v[6:7] op_sel_hi:[1,0]
	v_pk_mul_f32 v[4:5], v[54:55], v[6:7] op_sel_hi:[1,0]
	global_store_dwordx4 v[8:9], v[2:5], off offset:128
	s_nop 1
	v_pk_mul_f32 v[2:3], v[60:61], v[6:7] op_sel_hi:[1,0]
	v_pk_mul_f32 v[4:5], v[62:63], v[6:7] op_sel_hi:[1,0]
	global_store_dwordx4 v[8:9], v[2:5], off offset:192
	s_nop 1
	v_ashrrev_i32_e32 v3, 6, v107
	v_lshrrev_b32_e32 v2, 5, v3
	v_add_u32_e32 v5, -1, v3
	v_cmp_eq_u32_e64 s[60:61], v94, v2
	v_lshlrev_b32_e64 v2, v3, 1
	v_lshrrev_b32_e32 v6, 5, v5
	v_add_u32_e32 v4, -2, v3
	v_cndmask_b32_e64 v2, 0, v2, s[60:61]
	v_cmp_eq_u32_e64 s[60:61], v94, v6
	v_lshlrev_b32_e64 v5, v5, 1
	v_cmp_lt_i32_e32 vcc, 15, v3
	v_cndmask_b32_e64 v5, 0, v5, s[60:61]
	v_lshl_add_u32 v3, 2, v3, -1
	v_cmp_gt_i32_e64 s[60:61], v94, v4
	v_or3_b32 v2, v2, v100, v5
	v_cndmask_b32_e64 v3, 0, v3, s[44:45]
	s_or_b64 s[86:87], s[44:45], s[60:61]
	v_cmp_gt_i32_e64 s[60:61], v101, v4
	v_cmp_gt_i32_e64 s[62:63], v102, v4
	v_cmp_gt_i32_e64 s[64:65], v103, v4
	s_branch .LBB0_573
